# row loop: removed false store-completion waits (top vmcnt(4) x2, post-store vmcnt ladder bypassed when l>0)
# baseline (speedup 1.0000x reference)
; __device__ __forceinline__ float bf2f(unsigned b) { return __uint_as_float(b << 16); }
; __device__ __forceinline__ void phaseA(const Params& p, int l, unsigned char* lds, int wid0) {
;     ...
;     const int gw = blockIdx.x * 8 + wid, NGW = gridDim.x * 8;
;     const bf16* outb = (const bf16*)(ws + WS_OUT); bf16* hb = (bf16*)(ws + WS_H); float* xc = (float*)(ws + WS_XC);
;     const int nrows = (l < DEPTH) ? MROWS : MLAT;
;     for (int r0 = gw; r0 < nrows; r0 += 2 * NGW) {
;         const int r1 = r0 + NGW; const bool two = r1 < nrows;
;         f32x4 v[2][4], o[2][4]; const float* xs[2]; float* xd[2]; int cond[2]; int rr[2] = {r0, two ? r1 : r0};
; #pragma unroll
;         for (int k = 0; k < 2; ++k) { const int r = rr[k]; const bool isctx = r >= MLAT; cond[k] = isctx ? 2 : (r >> 13);
;             if (!isctx) { xs[k] = (l <= 1 ? p.in[I_X] : p.out) + (size_t)r * 1024; xd[k] = p.out + (size_t)r * 1024; }
;             else { xs[k] = (l <= 1 ? p.in[I_CTX] : xc) + (size_t)(r - MLAT) * 1024; xd[k] = xc + (size_t)(r - MLAT) * 1024; }
; #pragma unroll
;             for (int j = 0; j < 4; ++j) v[k][j] = *(const f32x4*)(xs[k] + 4 * lane + 256 * j);
;             if (l > 0) {
; #pragma unroll
;                 for (int j = 0; j < 4; ++j) { const u32x2 w = *(const u32x2*)(outb + (size_t)r * 1024 + 4 * lane + 256 * j); o[k][j] = (f32x4){bf2f(w.x & 0xffffu), bf2f(w.x >> 16), bf2f(w.y & 0xffffu), bf2f(w.y >> 16)}; } } }
.LBB0_558:
	v_readlane_b32 s0, v254, 46
	v_readlane_b32 s1, v254, 47
	s_or_b64 exec, exec, s[0:1]
	v_readlane_b32 s0, v250, 10
	v_readlane_b32 s1, v250, 11
	s_waitcnt lgkmcnt(0)
	s_barrier
	s_load_dword s24, s[0:1], 0x0
	s_movk_i32 s27, 0x4200
	v_readlane_b32 s4, v253, 55
	v_readlane_b32 s5, v253, 56
	s_waitcnt lgkmcnt(0)
	s_lshl_b32 s26, s24, 3
	s_cmp_lt_i32 s61, 21
	s_cselect_b64 s[0:1], -1, 0
	s_and_b64 s[34:35], s[0:1], exec
	s_cselect_b32 s27, s27, 0x4000
	s_cmp_ge_i32 s4, s27
	s_cbranch_scc1 .LBB0_572
	v_lshlrev_b32_e32 v32, 2, v72
	v_ashrrev_i32_e32 v33, 31, v32
	v_readlane_b32 s4, v251, 28
	v_lshlrev_b64 v[0:1], 1, v[32:33]
	v_readlane_b32 s5, v251, 29
	s_cmp_gt_i32 s79, 5
	s_cselect_b64 s[34:35], -1, 0
	v_lshl_add_u64 v[34:35], s[4:5], 0, v[0:1]
	v_readlane_b32 s4, v253, 7
	s_lshl_b32 s38, s24, 4
	v_readlane_b32 s5, v253, 8
	v_readlane_b32 s40, v250, 1
	s_cmp_lt_i32 s79, 11
	v_lshl_add_u64 v[36:37], s[4:5], 0, v[0:1]
	v_readlane_b32 s44, v250, 5
	v_readlane_b32 s4, v253, 21
	v_readlane_b32 s9, v253, 26
	s_cselect_b32 s72, s4, s44
	v_readlane_b32 s4, v251, 25
	v_readlane_b32 s45, v250, 6
	v_readlane_b32 s5, v253, 22
	v_readlane_b32 s8, v253, 25
	s_cselect_b32 s73, s9, s4
	v_readlane_b32 s4, v251, 24
	s_cselect_b32 s61, s5, s45
	s_cselect_b32 s74, s8, s4
	v_readlane_b32 s4, v253, 57
	v_readlane_b32 s5, v253, 58
	v_readlane_b32 s41, v250, 2
	v_readlane_b32 s42, v250, 3
	v_readlane_b32 s43, v250, 4
	v_readlane_b32 s20, v254, 40
	v_lshl_add_u64 v[38:39], s[4:5], 0, v[0:1]
	s_ashr_i32 s39, s38, 31
	v_readlane_b32 s4, v253, 55
	v_lshl_add_u32 v73, v72, 4, 0
	s_movk_i32 s86, 0x4000
	v_readlane_b32 s21, v254, 41
	s_lshl_b64 s[40:41], s[38:39], 11
	s_mov_b64 s[42:43], 0
	s_mov_b32 s75, s4
	v_readlane_b32 s46, v250, 7
	v_readlane_b32 s47, v250, 8
	v_readlane_b32 s6, v253, 23
	v_readlane_b32 s7, v253, 24
	v_readlane_b32 s10, v253, 27
	v_readlane_b32 s11, v253, 28
	v_readlane_b32 s12, v253, 29
	v_readlane_b32 s13, v253, 30
	v_readlane_b32 s14, v253, 31
	v_readlane_b32 s15, v253, 32
	v_readlane_b32 s16, v253, 33
	v_readlane_b32 s17, v253, 34
	v_readlane_b32 s18, v253, 35
	v_readlane_b32 s19, v253, 36
	v_readlane_b32 s5, v253, 56
	s_branch .LBB0_562
.Lrow_skipw:
	s_waitcnt vmcnt(0)
.LBB0_561:
	s_add_i32 s75, s75, s38
	s_add_u32 s42, s42, s38
	s_addc_u32 s43, s43, s39
	s_cmp_ge_i32 s75, s27
	v_lshl_add_u64 v[38:39], v[38:39], 0, s[40:41]
	s_cbranch_scc1 .LBB0_572
.LBB0_562:
	s_add_i32 s46, s75, 0xffffc000
	v_readlane_b32 s4, v253, 55
	v_readlane_b32 s5, v253, 56
	s_add_u32 s47, s4, s42
	s_addc_u32 s48, s5, s43
	s_cmpk_gt_i32 s75, 0x3fff
	s_cselect_b64 s[62:63], -1, 0
	s_and_b64 s[44:45], s[62:63], exec
	s_cselect_b32 s65, 0, s48
	s_cselect_b32 s64, s46, s47
	s_cselect_b32 s46, s73, s61
	s_cselect_b32 s47, s74, s72
	s_lshl_b64 s[44:45], s[64:65], 12
	s_add_u32 s44, s47, s44
	s_addc_u32 s45, s46, s45
	v_lshl_add_u64 v[0:1], v[32:33], 2, s[44:45]
	global_load_dwordx4 v[20:23], v[0:1], off
	global_load_dwordx4 v[8:11], v[0:1], off offset:1024
	s_waitcnt lgkmcnt(0)
	global_load_dwordx4 v[4:7], v[0:1], off offset:2048
	s_nop 0
	global_load_dwordx4 v[0:3], v[0:1], off offset:3072
	s_add_i32 s44, s26, s75
	s_cmp_lt_i32 s44, s27
	s_cselect_b64 s[46:47], -1, 0
	s_and_b64 s[48:49], s[46:47], exec
	s_cselect_b32 s48, s44, s75
	s_cmpk_gt_i32 s48, 0x3fff
	s_cselect_b64 s[54:55], -1, 0
	s_add_i32 s45, s48, 0xffffc000
	s_ashr_i32 s49, s48, 31
	s_and_b64 s[58:59], s[54:55], exec
	s_cselect_b32 s59, 0, s49
	s_cselect_b32 s58, s45, s48
	s_cselect_b32 s45, s73, s61
	s_cselect_b32 s82, s74, s72
	s_lshl_b64 s[76:77], s[58:59], 12
	s_add_u32 s76, s82, s76
	s_addc_u32 s77, s45, s77
	v_lshl_add_u64 v[12:13], v[32:33], 2, s[76:77]
	global_load_dwordx4 v[28:31], v[12:13], off
	global_load_dwordx4 v[24:27], v[12:13], off offset:1024
	global_load_dwordx4 v[16:19], v[12:13], off offset:2048
	s_nop 0
	global_load_dwordx4 v[12:15], v[12:13], off offset:3072
	v_readlane_b32 s4, v251, 25
	s_and_b64 vcc, exec, s[34:35]
	s_cbranch_vccz .LBB0_566
	global_load_dwordx2 v[100:101], v[38:39], off
	global_load_dwordx2 v[102:103], v[38:39], off offset:512
	global_load_dwordx2 v[104:105], v[38:39], off offset:1024
	global_load_dwordx2 v[106:107], v[38:39], off offset:1536
	s_lshl_b64 s[76:77], s[48:49], 11
	v_lshl_add_u64 v[40:41], v[34:35], 0, s[76:77]
	global_load_dwordx2 v[42:43], v[40:41], off
	global_load_dwordx2 v[60:61], v[40:41], off offset:512
	global_load_dwordx2 v[64:65], v[40:41], off offset:1024
	global_load_dwordx2 v[68:69], v[40:41], off offset:1536
	s_waitcnt vmcnt(7)
	v_lshlrev_b32_e32 v54, 16, v100
	v_and_b32_e32 v55, 0xffff0000, v100
	v_lshlrev_b32_e32 v58, 16, v101
	v_and_b32_e32 v59, 0xffff0000, v101
	s_waitcnt vmcnt(6)
	v_lshlrev_b32_e32 v52, 16, v102
	v_and_b32_e32 v53, 0xffff0000, v102
	v_lshlrev_b32_e32 v62, 16, v103
	v_and_b32_e32 v63, 0xffff0000, v103
	s_waitcnt vmcnt(5)
	v_lshlrev_b32_e32 v50, 16, v104
	v_and_b32_e32 v51, 0xffff0000, v104
	v_lshlrev_b32_e32 v66, 16, v105
	v_and_b32_e32 v67, 0xffff0000, v105
	s_waitcnt vmcnt(4)
	v_lshlrev_b32_e32 v48, 16, v106
	v_and_b32_e32 v49, 0xffff0000, v106
	v_lshlrev_b32_e32 v70, 16, v107
	v_and_b32_e32 v71, 0xffff0000, v107
	s_waitcnt vmcnt(3)
	v_lshlrev_b32_e32 v46, 16, v42
	v_and_b32_e32 v47, 0xffff0000, v42
	v_lshlrev_b32_e32 v56, 16, v43
	v_and_b32_e32 v57, 0xffff0000, v43
	s_waitcnt vmcnt(2)
	v_lshlrev_b32_e32 v44, 16, v60
	v_and_b32_e32 v45, 0xffff0000, v60
	v_lshlrev_b32_e32 v60, 16, v61
	v_and_b32_e32 v61, 0xffff0000, v61
	s_waitcnt vmcnt(1)
	v_lshlrev_b32_e32 v42, 16, v64
	v_and_b32_e32 v43, 0xffff0000, v64
	v_lshlrev_b32_e32 v64, 16, v65
	v_and_b32_e32 v65, 0xffff0000, v65
	s_waitcnt vmcnt(0)
	v_lshlrev_b32_e32 v40, 16, v68
	v_and_b32_e32 v41, 0xffff0000, v68
	v_lshlrev_b32_e32 v68, 16, v69
	v_and_b32_e32 v69, 0xffff0000, v69

; __device__ __forceinline__ unsigned cvt_pk_bf16(float lo, float hi) { unsigned r; asm volatile("v_cvt_pk_bf16_f32 %0, %1, %2" : "=v"(r) : "v"(lo), "v"(hi)); return r; }
; __device__ __forceinline__ void phaseA(const Params& p, int l, unsigned char* lds, int wid0) {
;     ...
;         if (l < DEPTH) { float ss[2];
; #pragma unroll
;             for (int k = 0; k < 2; ++k) { ss[k] = 0.f;
; #pragma unroll
;                 for (int j = 0; j < 4; ++j) ss[k] += (v[k][j][0] * v[k][j][0] + v[k][j][1] * v[k][j][1]) + (v[k][j][2] * v[k][j][2] + v[k][j][3] * v[k][j][3]); }
;             ss[0] = wave_sum(ss[0]); ss[1] = wave_sum(ss[1]);
; #pragma unroll
;             for (int k = 0; k < 2; ++k) { const float rinv = rsqrtf(ss[k] * (1.f / 1024.f) + EPSN);
;                 if (k == 0 || two) {
; #pragma unroll
;                     for (int j = 0; j < 4; ++j) { const f32x4 a = *(const f32x4*)(vA + cond[k] * 1024 + 4 * lane + 256 * j), sh = *(const f32x4*)(vSH + cond[k] * 1024 + 4 * lane + 256 * j);
;                         const f32x4 h = v[k][j] * rinv * a + sh; u32x2 w; w.x = pg8::cvt_pk_bf16(h[0], h[1]); w.y = pg8::cvt_pk_bf16(h[2], h[3]); *(u32x2*)(hb + (size_t)rr[k] * 1024 + 4 * lane + 256 * j) = w; } } } }
.LBB0_569:
	s_andn2_b64 vcc, exec, s[0:1]
	s_cbranch_vccnz .Lrow_skipw
	s_and_b64 vcc, exec, s[34:35]
	s_cbranch_vccnz .Lrow_nw
	s_waitcnt vmcnt(0)
.Lrow_nw:
	v_pk_mul_f32 v[76:77], v[22:23], v[22:23]
	v_pk_mul_f32 v[78:79], v[20:21], v[20:21]
	s_mov_b32 s48, 0xf6800000
	v_pk_mov_b32 v[80:81], v[78:79], v[76:77] op_sel:[1,0]
	v_mov_b32_e32 v79, v77
	v_pk_add_f32 v[76:77], v[80:81], v[78:79]
	v_pk_mul_f32 v[78:79], v[10:11], v[10:11]
	v_pk_add_f32 v[76:77], v[76:77], v[76:77] op_sel_hi:[0,1]
	v_pk_mul_f32 v[80:81], v[8:9], v[8:9]
	v_mul_f32_e32 v76, v4, v4
	v_pk_mov_b32 v[82:83], v[80:81], v[78:79] op_sel:[1,0]
	v_mov_b32_e32 v81, v79
	v_pk_add_f32 v[78:79], v[82:83], v[80:81]
	v_pk_fma_f32 v[80:81], v[4:5], v[4:5], v[76:77] op_sel_hi:[1,1,0]
	v_mul_f32_e32 v76, v6, v6
	v_pk_add_f32 v[78:79], v[78:79], v[78:79] op_sel_hi:[0,1]
	v_pk_fma_f32 v[82:83], v[6:7], v[6:7], v[76:77] op_sel_hi:[1,1,0]
	v_mul_f32_e32 v80, v0, v0
	v_mul_f32_e32 v82, v1, v1
	v_mul_f32_e32 v78, v2, v2
	v_mul_f32_e32 v76, v3, v3
	v_pk_add_f32 v[80:81], v[80:81], v[82:83]
	v_pk_add_f32 v[76:77], v[78:79], v[76:77]
	v_and_b32_e32 v79, 64, v220
	v_pk_add_f32 v[76:77], v[80:81], v[76:77]
	v_add_u32_e32 v79, 64, v79
	v_xor_b32_e32 v80, 1, v220
	v_cmp_lt_i32_e32 vcc, v80, v79
	v_add_f32_e32 v75, v76, v77
	v_mul_f32_e32 v76, v29, v29
	v_mul_f32_e32 v77, v31, v31
	v_cndmask_b32_e32 v80, v220, v80, vcc
	v_fmac_f32_e32 v76, v28, v28
	v_fmac_f32_e32 v77, v30, v30
	v_lshlrev_b32_e32 v80, 2, v80
	v_add_f32_e32 v76, v76, v77
	v_mul_f32_e32 v77, v25, v25
	v_mul_f32_e32 v78, v27, v27
	ds_bpermute_b32 v81, v80, v75
	v_fmac_f32_e32 v77, v24, v24
	v_fmac_f32_e32 v78, v26, v26
	v_add_f32_e32 v77, v77, v78
	v_xor_b32_e32 v78, 2, v220
	v_cmp_lt_i32_e32 vcc, v78, v79
	s_waitcnt lgkmcnt(0)
	v_add_f32_e32 v75, v75, v81
	v_add_f32_e32 v76, v76, v77
	v_cndmask_b32_e32 v78, v220, v78, vcc
	v_lshlrev_b32_e32 v78, 2, v78
	ds_bpermute_b32 v81, v78, v75
	v_mul_f32_e32 v77, v17, v17
	v_mul_f32_e32 v82, v19, v19
	v_fmac_f32_e32 v77, v16, v16
	v_fmac_f32_e32 v82, v18, v18
	s_waitcnt lgkmcnt(0)
	v_add_f32_e32 v75, v75, v81
	v_xor_b32_e32 v81, 4, v220
	v_cmp_lt_i32_e32 vcc, v81, v79
	v_add_f32_e32 v77, v77, v82
	v_add_f32_e32 v76, v76, v77
	v_cndmask_b32_e32 v81, v220, v81, vcc
	v_lshlrev_b32_e32 v81, 2, v81
	ds_bpermute_b32 v82, v81, v75
	v_mul_f32_e32 v77, v13, v13
	v_mul_f32_e32 v83, v15, v15
	v_fmac_f32_e32 v77, v12, v12
	v_fmac_f32_e32 v83, v14, v14
	v_add_f32_e32 v77, v77, v83
	s_waitcnt lgkmcnt(0)
	v_add_f32_e32 v75, v75, v82
	v_xor_b32_e32 v82, 8, v220
	v_add_f32_e32 v76, v76, v77
	v_cmp_lt_i32_e32 vcc, v82, v79
	ds_bpermute_b32 v77, v80, v76
	v_xor_b32_e32 v80, 16, v220
	v_cndmask_b32_e32 v82, v220, v82, vcc
	v_lshlrev_b32_e32 v82, 2, v82
	ds_bpermute_b32 v84, v82, v75
	s_waitcnt lgkmcnt(1)
	v_add_f32_e32 v76, v76, v77
	v_cmp_lt_i32_e32 vcc, v80, v79
	ds_bpermute_b32 v77, v78, v76
	s_waitcnt lgkmcnt(1)
	v_add_f32_e32 v75, v75, v84
	v_cndmask_b32_e32 v80, v220, v80, vcc
	v_lshlrev_b32_e32 v78, 2, v80
	ds_bpermute_b32 v80, v78, v75
	s_waitcnt lgkmcnt(1)
	v_add_f32_e32 v76, v76, v77
	ds_bpermute_b32 v77, v81, v76
	s_waitcnt lgkmcnt(1)
	v_add_f32_e32 v75, v75, v80
	v_xor_b32_e32 v80, 32, v220
	v_cmp_lt_i32_e32 vcc, v80, v79
	s_waitcnt lgkmcnt(0)
	v_add_f32_e32 v76, v76, v77
	ds_bpermute_b32 v77, v82, v76
	v_cndmask_b32_e32 v79, v220, v80, vcc
	v_lshlrev_b32_e32 v85, 2, v79
	ds_bpermute_b32 v79, v85, v75
	s_waitcnt lgkmcnt(1)
	v_add_f32_e32 v76, v76, v77
	ds_bpermute_b32 v77, v78, v76
	s_waitcnt lgkmcnt(1)
	v_add_f32_e32 v75, v75, v79
	v_fmamk_f32 v75, v75, 0x3a800000, v211
	v_mul_f32_e32 v78, 0x4b800000, v75
	v_cmp_gt_f32_e32 vcc, s87, v75
	s_nop 1
	v_cndmask_b32_e32 v75, v75, v78, vcc
	v_rsq_f32_e32 v84, v75
	s_waitcnt lgkmcnt(0)
	v_add_f32_e32 v75, v76, v77
	ds_read_b128 v[76:79], v74
	ds_read_b128 v[80:83], v74 offset:12288
	v_mul_f32_e32 v86, 0x45800000, v84
	v_cndmask_b32_e32 v84, v84, v86, vcc
	v_pk_mul_f32 v[20:21], v[20:21], v[84:85] op_sel_hi:[1,0]
	v_pk_mul_f32 v[22:23], v[22:23], v[84:85] op_sel_hi:[1,0]
	s_waitcnt lgkmcnt(0)
	v_pk_fma_f32 v[20:21], v[76:77], v[20:21], v[80:81]
	v_pk_fma_f32 v[22:23], v[78:79], v[22:23], v[82:83]
	v_cvt_pk_bf16_f32 v80, v20, v21
	v_add_co_u32_e32 v82, vcc, s48, v38
	v_cvt_pk_bf16_f32 v81, v22, v23
	ds_read_b128 v[20:23], v74 offset:1024
	ds_read_b128 v[76:79], v74 offset:13312
	v_pk_mul_f32 v[8:9], v[8:9], v[84:85] op_sel_hi:[1,0]
	v_pk_mul_f32 v[10:11], v[10:11], v[84:85] op_sel_hi:[1,0]
	v_addc_co_u32_e32 v83, vcc, -1, v39, vcc
	s_waitcnt lgkmcnt(0)
	v_pk_fma_f32 v[10:11], v[22:23], v[10:11], v[78:79]
	v_pk_fma_f32 v[8:9], v[20:21], v[8:9], v[76:77]
	global_store_dwordx2 v[82:83], v[80:81], off
	v_cvt_pk_bf16_f32 v76, v8, v9
	v_cvt_pk_bf16_f32 v77, v10, v11
	ds_read_b128 v[8:11], v74 offset:2048
	ds_read_b128 v[20:23], v74 offset:14336
	s_mov_b32 s48, 0xf6801000
	v_add_co_u32_e32 v78, vcc, s48, v38
	v_pk_mul_f32 v[6:7], v[6:7], v[84:85] op_sel_hi:[1,0]
	s_nop 0
	v_addc_co_u32_e32 v79, vcc, -1, v39, vcc
	v_pk_mul_f32 v[4:5], v[4:5], v[84:85] op_sel_hi:[1,0]
	s_waitcnt lgkmcnt(0)
	v_pk_fma_f32 v[6:7], v[6:7], v[10:11], v[22:23]
	global_store_dwordx2 v[78:79], v[76:77], off offset:-3584
	v_pk_fma_f32 v[4:5], v[4:5], v[8:9], v[20:21]
	v_pk_mul_f32 v[0:1], v[0:1], v[84:85] op_sel_hi:[1,0]
	v_cvt_pk_bf16_f32 v10, v4, v5
	v_cvt_pk_bf16_f32 v11, v6, v7
	ds_read_b128 v[6:9], v74 offset:3072
	ds_read_b128 v[20:23], v74 offset:15360
	ds_bpermute_b32 v4, v85, v75
	v_pk_mul_f32 v[2:3], v[2:3], v[84:85] op_sel_hi:[1,0]
	s_andn2_b64 vcc, exec, s[46:47]
	global_store_dwordx2 v[78:79], v[10:11], off offset:-3072
	s_waitcnt lgkmcnt(1)
	v_pk_fma_f32 v[0:1], v[0:1], v[6:7], v[20:21]
	v_pk_fma_f32 v[2:3], v[2:3], v[8:9], v[22:23]
	v_cvt_pk_bf16_f32 v0, v0, v1
	s_nop 0
	v_cvt_pk_bf16_f32 v1, v2, v3
	global_store_dwordx2 v[78:79], v[0:1], off offset:-2560
	s_cbranch_vccnz .LBB0_561
; __device__ __forceinline__ unsigned cvt_pk_bf16(float lo, float hi) { unsigned r; asm volatile("v_cvt_pk_bf16_f32 %0, %1, %2" : "=v"(r) : "v"(lo), "v"(hi)); return r; }
; __device__ __forceinline__ void phaseA(const Params& p, int l, unsigned char* lds, int wid0) {
;     ...
;             for (int k = 0; k < 2; ++k) { const float rinv = rsqrtf(ss[k] * (1.f / 1024.f) + EPSN);
;                 if (k == 0 || two) {
; #pragma unroll
;                     for (int j = 0; j < 4; ++j) { const f32x4 a = *(const f32x4*)(vA + cond[k] * 1024 + 4 * lane + 256 * j), sh = *(const f32x4*)(vSH + cond[k] * 1024 + 4 * lane + 256 * j);
;                         const f32x4 h = v[k][j] * rinv * a + sh; u32x2 w; w.x = pg8::cvt_pk_bf16(h[0], h[1]); w.y = pg8::cvt_pk_bf16(h[2], h[3]); *(u32x2*)(hb + (size_t)rr[k] * 1024 + 4 * lane + 256 * j) = w; } } } }
	s_waitcnt lgkmcnt(0)
	v_add_f32_e32 v0, v75, v4
	v_fmamk_f32 v0, v0, 0x3a800000, v211
	v_mul_f32_e32 v1, 0x4b800000, v0
	v_cmp_gt_f32_e32 vcc, s87, v0
	v_lshl_add_u32 v9, s45, 12, v73
	s_ashr_i32 s45, s44, 31
	v_cndmask_b32_e32 v0, v0, v1, vcc
	v_rsq_f32_e32 v8, v0
	ds_read_b128 v[0:3], v9
	ds_read_b128 v[4:7], v9 offset:12288
	s_lshl_b64 s[44:45], s[44:45], 11
	v_mul_f32_e32 v10, 0x45800000, v8
	v_cndmask_b32_e32 v8, v8, v10, vcc
	v_pk_mul_f32 v[10:11], v[28:29], v[8:9] op_sel_hi:[1,0]
	v_pk_mul_f32 v[20:21], v[30:31], v[8:9] op_sel_hi:[1,0]
	s_waitcnt lgkmcnt(0)
	v_pk_fma_f32 v[0:1], v[10:11], v[0:1], v[4:5]
	v_pk_fma_f32 v[2:3], v[20:21], v[2:3], v[6:7]
	v_cvt_pk_bf16_f32 v10, v0, v1
	v_lshl_add_u64 v[20:21], v[36:37], 0, s[44:45]
	v_cvt_pk_bf16_f32 v11, v2, v3
	ds_read_b128 v[0:3], v9 offset:1024
	ds_read_b128 v[4:7], v9 offset:13312
	global_store_dwordx2 v[20:21], v[10:11], off
	v_pk_mul_f32 v[10:11], v[24:25], v[8:9] op_sel_hi:[1,0]
	v_pk_mul_f32 v[22:23], v[26:27], v[8:9] op_sel_hi:[1,0]
	s_waitcnt lgkmcnt(0)
	v_pk_fma_f32 v[0:1], v[10:11], v[0:1], v[4:5]
	v_pk_fma_f32 v[2:3], v[22:23], v[2:3], v[6:7]
	v_cvt_pk_bf16_f32 v10, v0, v1
	s_nop 0
	v_cvt_pk_bf16_f32 v11, v2, v3
	ds_read_b128 v[0:3], v9 offset:2048
	ds_read_b128 v[4:7], v9 offset:14336
	global_store_dwordx2 v[20:21], v[10:11], off offset:512
	v_pk_mul_f32 v[10:11], v[16:17], v[8:9] op_sel_hi:[1,0]
	v_pk_mul_f32 v[16:17], v[18:19], v[8:9] op_sel_hi:[1,0]
	s_waitcnt lgkmcnt(0)
	v_pk_fma_f32 v[0:1], v[10:11], v[0:1], v[4:5]
	v_pk_fma_f32 v[2:3], v[16:17], v[2:3], v[6:7]
	v_cvt_pk_bf16_f32 v10, v0, v1
	s_nop 0
	v_cvt_pk_bf16_f32 v11, v2, v3
	ds_read_b128 v[0:3], v9 offset:3072
	ds_read_b128 v[4:7], v9 offset:15360
	global_store_dwordx2 v[20:21], v[10:11], off offset:1024
	v_pk_mul_f32 v[10:11], v[12:13], v[8:9] op_sel_hi:[1,0]
	v_pk_mul_f32 v[8:9], v[14:15], v[8:9] op_sel_hi:[1,0]
	s_waitcnt lgkmcnt(0)
	v_pk_fma_f32 v[0:1], v[10:11], v[0:1], v[4:5]
	v_pk_fma_f32 v[2:3], v[8:9], v[2:3], v[6:7]
	v_cvt_pk_bf16_f32 v0, v0, v1
	s_nop 0
	v_cvt_pk_bf16_f32 v1, v2, v3
	global_store_dwordx2 v[20:21], v[0:1], off offset:1536
	s_branch .LBB0_561
